# FFN-up epilogue stores of H carry the nt (streaming) cache hint
# speedup vs baseline: 1.0060x; 1.0008x over previous
; __device__ __forceinline__ float row_rs(const float* ss, int r, int fq) { const f32x4 a = *(const f32x4*)(ss + (size_t)r * 16 + 4 * fq);
;     float t = (a[0] + a[1]) + (a[2] + a[3]); t += __shfl_xor(t, 16); t += __shfl_xor(t, 32); return __builtin_amdgcn_rsqf(t * (1.0f / 1024.0f) + 1e-6f); }
;     __device__ __forceinline__ void operator()(const f32x4 (&acc)[2][2][4][2], const Unit& u, int wr, int wc, int fr, int fq) const {
;     ...
;         for (int ai = 0; ai < 2; ++ai)
; #pragma unroll
;             for (int m = 0; m < 4; ++m) rsv[ai][m] = row_rs(ss, row0 + ai * HALF + m * 16, fq);
; #pragma unroll
;         for (int ai = 0; ai < 2; ++ai)
; #pragma unroll
;             for (int m = 0; m < 4; ++m) { const int r = row0 + ai * HALF + m * 16; const float rs = rsv[ai][m], rs2 = rs * rs, nl = -1.4426950408889634f * rs;
;                 unsigned w[4];
; #pragma unroll
;                 for (int n = 0; n < 2; ++n) { const f32x4 g = acc[ai][0][m][n], gu = g * acc[ai][1][m][n] * rs2, ge = g * nl; float hv[4];
.LBB0_27:
	v_and_b32_e32 v133, 64, v236
	v_xor_b32_e32 v132, 16, v236
	v_add_u32_e32 v133, 64, v133
	v_cmp_lt_i32_e32 vcc, v132, v133
	v_lshl_add_u32 v160, s22, 8, v162
	v_ashrrev_i32_e32 v161, 31, v160
	v_cndmask_b32_e32 v132, v236, v132, vcc
	v_lshlrev_b32_e32 v167, 2, v132
	v_xor_b32_e32 v132, 32, v236
	v_cmp_lt_i32_e32 vcc, v132, v133
	v_or_b32_e32 v158, 16, v160
	v_ashrrev_i32_e32 v159, 31, v158
	v_cndmask_b32_e32 v132, v236, v132, vcc
	v_lshlrev_b32_e32 v166, 2, v132
	v_lshlrev_b64 v[132:133], 6, v[160:161]
	v_lshl_add_u64 v[132:133], v[140:141], 0, v[132:133]
	global_load_dwordx4 v[188:191], v[132:133], off
	v_lshlrev_b64 v[134:135], 6, v[158:159]
	v_lshl_add_u64 v[134:135], v[140:141], 0, v[134:135]
	global_load_dwordx4 v[192:195], v[134:135], off
	v_or_b32_e32 v156, 32, v160
	v_ashrrev_i32_e32 v157, 31, v156
	v_lshlrev_b64 v[132:133], 6, v[156:157]
	v_lshl_add_u64 v[132:133], v[140:141], 0, v[132:133]
	global_load_dwordx4 v[196:199], v[132:133], off
	v_or_b32_e32 v154, 48, v160
	v_ashrrev_i32_e32 v155, 31, v154
	v_lshlrev_b64 v[134:135], 6, v[154:155]
	v_lshl_add_u64 v[134:135], v[140:141], 0, v[134:135]
	global_load_dwordx4 v[200:203], v[134:135], off
	v_add_u32_e32 v152, 0x80, v160
	v_ashrrev_i32_e32 v153, 31, v152
	v_lshlrev_b64 v[132:133], 6, v[152:153]
	v_lshl_add_u64 v[132:133], v[140:141], 0, v[132:133]
	global_load_dwordx4 v[204:207], v[132:133], off
	v_add_u32_e32 v150, 0x90, v160
	v_ashrrev_i32_e32 v151, 31, v150
	v_lshlrev_b64 v[134:135], 6, v[150:151]
	v_lshl_add_u64 v[134:135], v[140:141], 0, v[134:135]
	global_load_dwordx4 v[208:211], v[134:135], off
	v_add_u32_e32 v148, 0xa0, v160
	v_ashrrev_i32_e32 v149, 31, v148
	v_lshlrev_b64 v[132:133], 6, v[148:149]
	v_lshl_add_u64 v[132:133], v[140:141], 0, v[132:133]
	global_load_dwordx4 v[212:215], v[132:133], off
	v_add_u32_e32 v146, 0xb0, v160
	v_ashrrev_i32_e32 v147, 31, v146
	v_lshlrev_b64 v[134:135], 6, v[146:147]
	v_lshl_add_u64 v[134:135], v[140:141], 0, v[134:135]
	global_load_dwordx4 v[216:219], v[134:135], off
	v_pk_mul_f32 v[124:125], v[128:129], v[124:125]
	v_pk_mul_f32 v[126:127], v[130:131], v[126:127]
	v_pk_mul_f32 v[116:117], v[120:121], v[116:117]
	v_pk_mul_f32 v[118:119], v[122:123], v[118:119]
	v_readlane_b32 s2, v255, 18
	v_readlane_b32 s3, v255, 19
	v_pk_mul_f32 v[108:109], v[112:113], v[108:109]
	v_pk_mul_f32 v[110:111], v[114:115], v[110:111]
	v_pk_mul_f32 v[100:101], v[104:105], v[100:101]
	v_pk_mul_f32 v[102:103], v[106:107], v[102:103]
	v_pk_mul_f32 v[92:93], v[96:97], v[92:93]
	v_pk_mul_f32 v[94:95], v[98:99], v[94:95]
	v_pk_mul_f32 v[84:85], v[88:89], v[84:85]
	v_pk_mul_f32 v[86:87], v[90:91], v[86:87]
	v_pk_mul_f32 v[76:77], v[80:81], v[76:77]
	v_pk_mul_f32 v[78:79], v[82:83], v[78:79]
	v_pk_mul_f32 v[68:69], v[72:73], v[68:69]
	v_pk_mul_f32 v[70:71], v[74:75], v[70:71]
	v_pk_mul_f32 v[60:61], v[64:65], v[60:61]
	v_pk_mul_f32 v[62:63], v[66:67], v[62:63]
	v_pk_mul_f32 v[52:53], v[56:57], v[52:53]
	v_pk_mul_f32 v[54:55], v[58:59], v[54:55]
	v_pk_mul_f32 v[44:45], v[48:49], v[44:45]
	v_pk_mul_f32 v[46:47], v[50:51], v[46:47]
	v_pk_mul_f32 v[36:37], v[40:41], v[36:37]
	v_pk_mul_f32 v[38:39], v[42:43], v[38:39]
	v_pk_mul_f32 v[28:29], v[32:33], v[28:29]
	v_pk_mul_f32 v[30:31], v[34:35], v[30:31]
	v_pk_mul_f32 v[20:21], v[24:25], v[20:21]
	v_pk_mul_f32 v[22:23], v[26:27], v[22:23]
	v_pk_mul_f32 v[12:13], v[16:17], v[12:13]
	v_pk_mul_f32 v[14:15], v[18:19], v[14:15]
	v_pk_mul_f32 v[4:5], v[8:9], v[4:5]
	v_pk_mul_f32 v[6:7], v[10:11], v[6:7]
	s_andn2_b64 vcc, exec, s[6:7]
	s_waitcnt vmcnt(0)
	v_add_f32_e32 v188, v188, v189
	v_add_f32_e32 v190, v190, v191
	v_add_f32_e32 v192, v192, v193
	v_add_f32_e32 v194, v194, v195
	v_add_f32_e32 v196, v196, v197
	v_add_f32_e32 v198, v198, v199
	v_add_f32_e32 v200, v200, v201
	v_add_f32_e32 v202, v202, v203
	v_add_f32_e32 v204, v204, v205
	v_add_f32_e32 v206, v206, v207
	v_add_f32_e32 v208, v208, v209
	v_add_f32_e32 v210, v210, v211
	v_add_f32_e32 v212, v212, v213
	v_add_f32_e32 v214, v214, v215
	v_add_f32_e32 v216, v216, v217
	v_add_f32_e32 v218, v218, v219
	v_add_f32_e32 v188, v188, v190
	v_add_f32_e32 v192, v192, v194
	v_add_f32_e32 v196, v196, v198
	v_add_f32_e32 v200, v200, v202
	v_add_f32_e32 v204, v204, v206
	v_add_f32_e32 v208, v208, v210
	v_add_f32_e32 v212, v212, v214
	v_add_f32_e32 v216, v216, v218
	ds_bpermute_b32 v189, v167, v188
	ds_bpermute_b32 v193, v167, v192
	ds_bpermute_b32 v197, v167, v196
	ds_bpermute_b32 v201, v167, v200
	ds_bpermute_b32 v205, v167, v204
	ds_bpermute_b32 v209, v167, v208
	ds_bpermute_b32 v213, v167, v212
	ds_bpermute_b32 v217, v167, v216
	s_waitcnt lgkmcnt(7)
	v_add_f32_e32 v188, v188, v189
	ds_bpermute_b32 v189, v166, v188
	s_waitcnt lgkmcnt(7)
	v_add_f32_e32 v192, v192, v193
	ds_bpermute_b32 v193, v166, v192
	s_waitcnt lgkmcnt(7)
	v_add_f32_e32 v196, v196, v197
	ds_bpermute_b32 v197, v166, v196
	s_waitcnt lgkmcnt(7)
	v_add_f32_e32 v200, v200, v201
	ds_bpermute_b32 v201, v166, v200
	s_waitcnt lgkmcnt(7)
	v_add_f32_e32 v204, v204, v205
	ds_bpermute_b32 v205, v166, v204
	s_waitcnt lgkmcnt(7)
	v_add_f32_e32 v208, v208, v209
	ds_bpermute_b32 v209, v166, v208
	s_waitcnt lgkmcnt(7)
	v_add_f32_e32 v212, v212, v213
	ds_bpermute_b32 v213, v166, v212
	s_waitcnt lgkmcnt(7)
	v_add_f32_e32 v216, v216, v217
	ds_bpermute_b32 v217, v166, v216
	s_waitcnt lgkmcnt(7)
	v_add_f32_e32 v188, v188, v189
	v_fmamk_f32 v188, v188, 0x3a800000, v237
	s_waitcnt lgkmcnt(6)
	v_add_f32_e32 v192, v192, v193
	v_fmamk_f32 v192, v192, 0x3a800000, v237
	s_waitcnt lgkmcnt(5)
	v_add_f32_e32 v196, v196, v197
	v_fmamk_f32 v196, v196, 0x3a800000, v237
	s_waitcnt lgkmcnt(4)
; __device__ __forceinline__ unsigned pk2(float lo, float hi) { f32x2 v = {lo, hi}; bf16x2_t b = __builtin_convertvector(v, bf16x2_t); return __builtin_bit_cast(unsigned, b); }
;     __device__ __forceinline__ void operator()(const f32x4 (&acc)[2][2][4][2], const Unit& u, int wr, int wc, int fr, int fq) const {
;     ...
;             for (int m = 0; m < 4; ++m) { const int r = row0 + ai * HALF + m * 16; const float rs = rsv[ai][m], rs2 = rs * rs, nl = -1.4426950408889634f * rs;
;                 unsigned w[4];
; #pragma unroll
;                 for (int n = 0; n < 2; ++n) { const f32x4 g = acc[ai][0][m][n], gu = g * acc[ai][1][m][n] * rs2, ge = g * nl; float hv[4];
; #pragma unroll
;                     for (int e = 0; e < 4; ++e) hv[e] = gu[e] * __builtin_amdgcn_rcpf(1.0f + __builtin_amdgcn_exp2f(ge[e]));
;                     w[2 * n] = pk2(hv[0], hv[1]); w[2 * n + 1] = pk2(hv[2], hv[3]); }
;                 *(u32x4*)(H + (size_t)r * ldh + col0) = (u32x4){w[0], w[1], w[2], w[3]}; }
	v_add_f32_e32 v200, v200, v201
	v_fmamk_f32 v200, v200, 0x3a800000, v237
	s_waitcnt lgkmcnt(3)
	v_add_f32_e32 v204, v204, v205
	v_fmamk_f32 v204, v204, 0x3a800000, v237
	s_waitcnt lgkmcnt(2)
	v_add_f32_e32 v208, v208, v209
	v_fmamk_f32 v208, v208, 0x3a800000, v237
	s_waitcnt lgkmcnt(1)
	v_add_f32_e32 v212, v212, v213
	v_fmamk_f32 v212, v212, 0x3a800000, v237
	s_waitcnt lgkmcnt(0)
	v_add_f32_e32 v216, v216, v217
	v_fmamk_f32 v216, v216, 0x3a800000, v237
	v_rsq_f32_e32 v161, v188
	v_rsq_f32_e32 v159, v192
	v_rsq_f32_e32 v157, v196
	v_rsq_f32_e32 v155, v200
	v_rsq_f32_e32 v153, v204
	v_rsq_f32_e32 v151, v208
	v_rsq_f32_e32 v149, v212
	v_rsq_f32_e32 v132, v216
	v_mul_f32_e32 v168, 0xbfb8aa3b, v161
	v_pk_mul_f32 v[172:173], v[128:129], v[168:169] op_sel_hi:[1,0]
	v_pk_mul_f32 v[170:171], v[130:131], v[168:169] op_sel_hi:[1,0]
	v_lshl_or_b32 v134, s54, 7, v164
	v_exp_f32_e32 v128, v170
	v_exp_f32_e32 v129, v171
	v_add_f32_e32 v128, 1.0, v128
	v_rcp_f32_e32 v128, v128
	v_mul_f32_e32 v166, v161, v161
	v_exp_f32_e32 v133, v172
	v_add_f32_e32 v129, 1.0, v129
	v_rcp_f32_e32 v129, v129
	v_pk_mul_f32 v[124:125], v[124:125], v[166:167] op_sel_hi:[1,0]
	v_add_f32_e32 v133, 1.0, v133
	v_rcp_f32_e32 v172, v133
	v_exp_f32_e32 v133, v173
	v_pk_mul_f32 v[126:127], v[126:127], v[166:167] op_sel_hi:[1,0]
	v_pk_mul_f32 v[116:117], v[116:117], v[166:167] op_sel_hi:[1,0]
	v_pk_mul_f32 v[126:127], v[126:127], v[128:129]
	v_add_f32_e32 v133, 1.0, v133
	v_rcp_f32_e32 v173, v133
	v_pk_mul_f32 v[128:129], v[120:121], v[168:169] op_sel_hi:[1,0]
	v_pk_mul_f32 v[118:119], v[118:119], v[166:167] op_sel_hi:[1,0]
	v_exp_f32_e32 v128, v128
	v_pk_mul_f32 v[124:125], v[124:125], v[172:173]
	v_exp_f32_e32 v129, v129
	v_cvt_pk_bf16_f32 v124, v124, v125
	v_cvt_pk_bf16_f32 v125, v126, v127
	v_pk_mul_f32 v[126:127], v[122:123], v[168:169] op_sel_hi:[1,0]
	v_add_f32_e32 v128, 1.0, v128
	v_exp_f32_e32 v120, v126
	v_exp_f32_e32 v121, v127
	v_add_f32_e32 v129, 1.0, v129
	v_rcp_f32_e32 v128, v128
	v_rcp_f32_e32 v129, v129
	v_add_f32_e32 v120, 1.0, v120
	v_add_f32_e32 v121, 1.0, v121
	v_rcp_f32_e32 v120, v120
	v_rcp_f32_e32 v121, v121
	v_pk_mul_f32 v[116:117], v[116:117], v[128:129]
	v_ashrrev_i32_e32 v135, 31, v134
	v_cvt_pk_bf16_f32 v126, v116, v117
	v_pk_mul_f32 v[118:119], v[118:119], v[120:121]
	v_mov_b64_e32 v[116:117], s[2:3]
	v_cvt_pk_bf16_f32 v127, v118, v119
	v_mad_i64_i32 v[120:121], s[2:3], v160, s33, v[116:117]
	v_lshlrev_b64 v[118:119], 1, v[134:135]
	v_lshl_add_u64 v[120:121], v[120:121], 0, v[118:119]
	v_mul_f32_e32 v122, 0xbfb8aa3b, v159
	global_store_dwordx4 v[120:121], v[124:127], off nt
	v_mul_f32_e32 v120, v159, v159
	s_nop 0
	v_pk_mul_f32 v[126:127], v[112:113], v[122:123] op_sel_hi:[1,0]
	v_pk_mul_f32 v[124:125], v[114:115], v[122:123] op_sel_hi:[1,0]
	v_exp_f32_e32 v121, v126
	v_exp_f32_e32 v112, v124
	v_exp_f32_e32 v113, v125
	v_add_f32_e32 v121, 1.0, v121
	v_rcp_f32_e32 v126, v121
	v_exp_f32_e32 v121, v127
	v_add_f32_e32 v112, 1.0, v112
	v_add_f32_e32 v113, 1.0, v113
	v_rcp_f32_e32 v112, v112
	v_add_f32_e32 v121, 1.0, v121
	v_rcp_f32_e32 v127, v121
	v_rcp_f32_e32 v113, v113
	v_pk_mul_f32 v[108:109], v[108:109], v[120:121] op_sel_hi:[1,0]
	v_pk_mul_f32 v[110:111], v[110:111], v[120:121] op_sel_hi:[1,0]
	v_pk_mul_f32 v[108:109], v[108:109], v[126:127]
	v_pk_mul_f32 v[110:111], v[110:111], v[112:113]
	v_cvt_pk_bf16_f32 v108, v108, v109
	v_cvt_pk_bf16_f32 v109, v110, v111
	v_pk_mul_f32 v[110:111], v[106:107], v[122:123] op_sel_hi:[1,0]
	v_pk_mul_f32 v[112:113], v[104:105], v[122:123] op_sel_hi:[1,0]
	v_exp_f32_e32 v104, v110
	v_exp_f32_e32 v112, v112
	v_exp_f32_e32 v113, v113
	v_exp_f32_e32 v105, v111
	v_add_f32_e32 v104, 1.0, v104
	v_add_f32_e32 v112, 1.0, v112
	v_add_f32_e32 v113, 1.0, v113
	v_add_f32_e32 v105, 1.0, v105
	v_rcp_f32_e32 v112, v112
	v_rcp_f32_e32 v113, v113
	v_rcp_f32_e32 v104, v104
	v_rcp_f32_e32 v105, v105
	v_pk_mul_f32 v[100:101], v[100:101], v[120:121] op_sel_hi:[1,0]
	v_pk_mul_f32 v[102:103], v[102:103], v[120:121] op_sel_hi:[1,0]
	v_pk_mul_f32 v[100:101], v[100:101], v[112:113]
	v_pk_mul_f32 v[102:103], v[102:103], v[104:105]
	v_cvt_pk_bf16_f32 v110, v100, v101
	v_cvt_pk_bf16_f32 v111, v102, v103
	v_mad_i64_i32 v[100:101], s[2:3], v158, s33, v[116:117]
	v_mul_f32_e32 v102, 0xbfb8aa3b, v157
	v_lshl_add_u64 v[100:101], v[100:101], 0, v[118:119]
	v_pk_mul_f32 v[106:107], v[96:97], v[102:103] op_sel_hi:[1,0]
	global_store_dwordx4 v[100:101], v[108:111], off nt
	v_exp_f32_e32 v101, v106
	v_pk_mul_f32 v[104:105], v[98:99], v[102:103] op_sel_hi:[1,0]
	v_mul_f32_e32 v100, v157, v157
	v_exp_f32_e32 v96, v104
	v_add_f32_e32 v101, 1.0, v101
	v_rcp_f32_e32 v106, v101
	v_exp_f32_e32 v101, v107
	v_exp_f32_e32 v97, v105
	v_add_f32_e32 v96, 1.0, v96
	v_rcp_f32_e32 v96, v96
	v_add_f32_e32 v101, 1.0, v101
	v_add_f32_e32 v97, 1.0, v97
	v_rcp_f32_e32 v107, v101
	v_rcp_f32_e32 v97, v97
	v_pk_mul_f32 v[92:93], v[92:93], v[100:101] op_sel_hi:[1,0]
	v_pk_mul_f32 v[94:95], v[94:95], v[100:101] op_sel_hi:[1,0]
	v_pk_mul_f32 v[92:93], v[92:93], v[106:107]
	v_pk_mul_f32 v[94:95], v[94:95], v[96:97]
	v_cvt_pk_bf16_f32 v92, v92, v93
	v_cvt_pk_bf16_f32 v93, v94, v95
	v_pk_mul_f32 v[94:95], v[90:91], v[102:103] op_sel_hi:[1,0]
	v_pk_mul_f32 v[96:97], v[88:89], v[102:103] op_sel_hi:[1,0]
	v_exp_f32_e32 v88, v94
	v_exp_f32_e32 v96, v96
	v_exp_f32_e32 v97, v97
	v_exp_f32_e32 v89, v95
	v_add_f32_e32 v88, 1.0, v88
	v_add_f32_e32 v96, 1.0, v96
	v_add_f32_e32 v97, 1.0, v97
	v_add_f32_e32 v89, 1.0, v89
	v_rcp_f32_e32 v96, v96
	v_rcp_f32_e32 v97, v97
	v_rcp_f32_e32 v88, v88
	v_rcp_f32_e32 v89, v89
	v_pk_mul_f32 v[84:85], v[84:85], v[100:101] op_sel_hi:[1,0]
; __device__ __forceinline__ unsigned pk2(float lo, float hi) { f32x2 v = {lo, hi}; bf16x2_t b = __builtin_convertvector(v, bf16x2_t); return __builtin_bit_cast(unsigned, b); }
;     __device__ __forceinline__ void operator()(const f32x4 (&acc)[2][2][4][2], const Unit& u, int wr, int wc, int fr, int fq) const {
;     ...
;             for (int m = 0; m < 4; ++m) { const int r = row0 + ai * HALF + m * 16; const float rs = rsv[ai][m], rs2 = rs * rs, nl = -1.4426950408889634f * rs;
;                 unsigned w[4];
; #pragma unroll
;                 for (int n = 0; n < 2; ++n) { const f32x4 g = acc[ai][0][m][n], gu = g * acc[ai][1][m][n] * rs2, ge = g * nl; float hv[4];
; #pragma unroll
;                     for (int e = 0; e < 4; ++e) hv[e] = gu[e] * __builtin_amdgcn_rcpf(1.0f + __builtin_amdgcn_exp2f(ge[e]));
;                     w[2 * n] = pk2(hv[0], hv[1]); w[2 * n + 1] = pk2(hv[2], hv[3]); }
;                 *(u32x4*)(H + (size_t)r * ldh + col0) = (u32x4){w[0], w[1], w[2], w[3]}; }
	v_pk_mul_f32 v[86:87], v[86:87], v[100:101] op_sel_hi:[1,0]
	v_pk_mul_f32 v[84:85], v[84:85], v[96:97]
	v_pk_mul_f32 v[86:87], v[86:87], v[88:89]
	v_cvt_pk_bf16_f32 v94, v84, v85
	v_cvt_pk_bf16_f32 v95, v86, v87
	v_mad_i64_i32 v[84:85], s[2:3], v156, s33, v[116:117]
	v_mul_f32_e32 v86, 0xbfb8aa3b, v155
	v_lshl_add_u64 v[84:85], v[84:85], 0, v[118:119]
	v_pk_mul_f32 v[90:91], v[80:81], v[86:87] op_sel_hi:[1,0]
	global_store_dwordx4 v[84:85], v[92:95], off nt
	v_exp_f32_e32 v85, v90
	v_pk_mul_f32 v[88:89], v[82:83], v[86:87] op_sel_hi:[1,0]
	v_mul_f32_e32 v84, v155, v155
	v_exp_f32_e32 v80, v88
	v_add_f32_e32 v85, 1.0, v85
	v_rcp_f32_e32 v90, v85
	v_exp_f32_e32 v85, v91
	v_exp_f32_e32 v81, v89
	v_add_f32_e32 v80, 1.0, v80
	v_rcp_f32_e32 v80, v80
	v_add_f32_e32 v85, 1.0, v85
	v_add_f32_e32 v81, 1.0, v81
	v_rcp_f32_e32 v91, v85
	v_rcp_f32_e32 v81, v81
	v_pk_mul_f32 v[76:77], v[76:77], v[84:85] op_sel_hi:[1,0]
	v_pk_mul_f32 v[78:79], v[78:79], v[84:85] op_sel_hi:[1,0]
	v_pk_mul_f32 v[76:77], v[76:77], v[90:91]
	v_pk_mul_f32 v[78:79], v[78:79], v[80:81]
	v_cvt_pk_bf16_f32 v76, v76, v77
	v_cvt_pk_bf16_f32 v77, v78, v79
	v_pk_mul_f32 v[78:79], v[74:75], v[86:87] op_sel_hi:[1,0]
	v_pk_mul_f32 v[80:81], v[72:73], v[86:87] op_sel_hi:[1,0]
	v_exp_f32_e32 v72, v78
	v_exp_f32_e32 v80, v80
	v_exp_f32_e32 v81, v81
	v_exp_f32_e32 v73, v79
	v_add_f32_e32 v72, 1.0, v72
	v_add_f32_e32 v80, 1.0, v80
	v_add_f32_e32 v81, 1.0, v81
	v_add_f32_e32 v73, 1.0, v73
	v_rcp_f32_e32 v80, v80
	v_rcp_f32_e32 v81, v81
	v_rcp_f32_e32 v72, v72
	v_rcp_f32_e32 v73, v73
	v_pk_mul_f32 v[68:69], v[68:69], v[84:85] op_sel_hi:[1,0]
	v_pk_mul_f32 v[70:71], v[70:71], v[84:85] op_sel_hi:[1,0]
	v_pk_mul_f32 v[68:69], v[68:69], v[80:81]
	v_pk_mul_f32 v[70:71], v[70:71], v[72:73]
	v_cvt_pk_bf16_f32 v78, v68, v69
	v_cvt_pk_bf16_f32 v79, v70, v71
	v_mad_i64_i32 v[68:69], s[2:3], v154, s33, v[116:117]
	v_mul_f32_e32 v70, 0xbfb8aa3b, v153
	v_lshl_add_u64 v[68:69], v[68:69], 0, v[118:119]
	v_pk_mul_f32 v[74:75], v[64:65], v[70:71] op_sel_hi:[1,0]
	global_store_dwordx4 v[68:69], v[76:79], off nt
	v_exp_f32_e32 v69, v74
	v_pk_mul_f32 v[72:73], v[66:67], v[70:71] op_sel_hi:[1,0]
	v_mul_f32_e32 v68, v153, v153
	v_exp_f32_e32 v64, v72
	v_add_f32_e32 v69, 1.0, v69
	v_rcp_f32_e32 v74, v69
	v_exp_f32_e32 v69, v75
	v_exp_f32_e32 v65, v73
	v_add_f32_e32 v64, 1.0, v64
	v_rcp_f32_e32 v64, v64
	v_add_f32_e32 v69, 1.0, v69
	v_add_f32_e32 v65, 1.0, v65
	v_rcp_f32_e32 v75, v69
	v_rcp_f32_e32 v65, v65
	v_pk_mul_f32 v[60:61], v[60:61], v[68:69] op_sel_hi:[1,0]
	v_pk_mul_f32 v[62:63], v[62:63], v[68:69] op_sel_hi:[1,0]
	v_pk_mul_f32 v[60:61], v[60:61], v[74:75]
	v_pk_mul_f32 v[62:63], v[62:63], v[64:65]
	v_cvt_pk_bf16_f32 v60, v60, v61
	v_cvt_pk_bf16_f32 v61, v62, v63
	v_pk_mul_f32 v[62:63], v[58:59], v[70:71] op_sel_hi:[1,0]
	v_pk_mul_f32 v[64:65], v[56:57], v[70:71] op_sel_hi:[1,0]
	v_exp_f32_e32 v56, v62
	v_exp_f32_e32 v64, v64
	v_exp_f32_e32 v65, v65
	v_exp_f32_e32 v57, v63
	v_add_f32_e32 v56, 1.0, v56
	v_add_f32_e32 v64, 1.0, v64
	v_add_f32_e32 v65, 1.0, v65
	v_add_f32_e32 v57, 1.0, v57
	v_rcp_f32_e32 v64, v64
	v_rcp_f32_e32 v65, v65
	v_rcp_f32_e32 v56, v56
	v_rcp_f32_e32 v57, v57
	v_pk_mul_f32 v[52:53], v[52:53], v[68:69] op_sel_hi:[1,0]
	v_pk_mul_f32 v[54:55], v[54:55], v[68:69] op_sel_hi:[1,0]
	v_pk_mul_f32 v[52:53], v[52:53], v[64:65]
	v_pk_mul_f32 v[54:55], v[54:55], v[56:57]
	v_cvt_pk_bf16_f32 v62, v52, v53
	v_cvt_pk_bf16_f32 v63, v54, v55
	v_mad_i64_i32 v[52:53], s[2:3], v152, s33, v[116:117]
	v_mul_f32_e32 v54, 0xbfb8aa3b, v151
	v_lshl_add_u64 v[52:53], v[52:53], 0, v[118:119]
	v_pk_mul_f32 v[58:59], v[48:49], v[54:55] op_sel_hi:[1,0]
	global_store_dwordx4 v[52:53], v[60:63], off nt
	v_exp_f32_e32 v53, v58
	v_pk_mul_f32 v[56:57], v[50:51], v[54:55] op_sel_hi:[1,0]
	v_mul_f32_e32 v52, v151, v151
	v_exp_f32_e32 v48, v56
	v_add_f32_e32 v53, 1.0, v53
	v_rcp_f32_e32 v58, v53
	v_exp_f32_e32 v53, v59
	v_exp_f32_e32 v49, v57
	v_add_f32_e32 v48, 1.0, v48
	v_rcp_f32_e32 v48, v48
	v_add_f32_e32 v53, 1.0, v53
	v_add_f32_e32 v49, 1.0, v49
	v_rcp_f32_e32 v59, v53
	v_rcp_f32_e32 v49, v49
	v_pk_mul_f32 v[44:45], v[44:45], v[52:53] op_sel_hi:[1,0]
	v_pk_mul_f32 v[46:47], v[46:47], v[52:53] op_sel_hi:[1,0]
	v_pk_mul_f32 v[44:45], v[44:45], v[58:59]
; __device__ __forceinline__ unsigned pk2(float lo, float hi) { f32x2 v = {lo, hi}; bf16x2_t b = __builtin_convertvector(v, bf16x2_t); return __builtin_bit_cast(unsigned, b); }
; #define PG8_BAR __builtin_amdgcn_s_barrier()
;     __device__ __forceinline__ void operator()(const f32x4 (&acc)[2][2][4][2], const Unit& u, int wr, int wc, int fr, int fq) const {
;     ...
;             for (int m = 0; m < 4; ++m) { const int r = row0 + ai * HALF + m * 16; const float rs = rsv[ai][m], rs2 = rs * rs, nl = -1.4426950408889634f * rs;
;                 unsigned w[4];
; #pragma unroll
;                 for (int n = 0; n < 2; ++n) { const f32x4 g = acc[ai][0][m][n], gu = g * acc[ai][1][m][n] * rs2, ge = g * nl; float hv[4];
; #pragma unroll
;                     for (int e = 0; e < 4; ++e) hv[e] = gu[e] * __builtin_amdgcn_rcpf(1.0f + __builtin_amdgcn_exp2f(ge[e]));
;                     w[2 * n] = pk2(hv[0], hv[1]); w[2 * n + 1] = pk2(hv[2], hv[3]); }
;                 *(u32x4*)(H + (size_t)r * ldh + col0) = (u32x4){w[0], w[1], w[2], w[3]}; }
; template <class Epi, class Sched, bool ALIGN_EPI = false, bool SP2 = false>
; __device__ __forceinline__ void gemm_phase(PG8_LAS unsigned char* lds, const Gemm g, const Sched& S, const Epi& E, const int tid_) {
;     ...
;         if constexpr (!Epi::AFTER_DRAIN) { E(acc, cur, wr, wc, fr, fq); S.done(cur); }
;         if (!has_next) break;
; #pragma unroll
;         for (int a = 0; a < 2; ++a)
; #pragma unroll
;             for (int b = 0; b < 2; ++b)
; #pragma unroll
;                 for (int m = 0; m < 4; ++m)
; #pragma unroll
;                     for (int n = 0; n < 2; ++n) acc[a][b][m][n] = (f32x4){0.f, 0.f, 0.f, 0.f};
;         cur = nxt; cA = nA; cB = nB; ++ui;
;         if constexpr (ALIGN_EPI) { if (wr == 1) PG8_BAR; }
	v_pk_mul_f32 v[46:47], v[46:47], v[48:49]
	v_cvt_pk_bf16_f32 v44, v44, v45
	v_cvt_pk_bf16_f32 v45, v46, v47
	v_pk_mul_f32 v[46:47], v[42:43], v[54:55] op_sel_hi:[1,0]
	v_pk_mul_f32 v[48:49], v[40:41], v[54:55] op_sel_hi:[1,0]
	v_exp_f32_e32 v40, v46
	v_exp_f32_e32 v48, v48
	v_exp_f32_e32 v49, v49
	v_exp_f32_e32 v41, v47
	v_add_f32_e32 v40, 1.0, v40
	v_add_f32_e32 v48, 1.0, v48
	v_add_f32_e32 v49, 1.0, v49
	v_add_f32_e32 v41, 1.0, v41
	v_rcp_f32_e32 v48, v48
	v_rcp_f32_e32 v49, v49
	v_rcp_f32_e32 v40, v40
	v_rcp_f32_e32 v41, v41
	v_pk_mul_f32 v[36:37], v[36:37], v[52:53] op_sel_hi:[1,0]
	v_pk_mul_f32 v[38:39], v[38:39], v[52:53] op_sel_hi:[1,0]
	v_pk_mul_f32 v[36:37], v[36:37], v[48:49]
	v_pk_mul_f32 v[38:39], v[38:39], v[40:41]
	v_cvt_pk_bf16_f32 v46, v36, v37
	v_cvt_pk_bf16_f32 v47, v38, v39
	v_mad_i64_i32 v[36:37], s[2:3], v150, s33, v[116:117]
	v_mul_f32_e32 v38, 0xbfb8aa3b, v149
	v_lshl_add_u64 v[36:37], v[36:37], 0, v[118:119]
	v_pk_mul_f32 v[42:43], v[32:33], v[38:39] op_sel_hi:[1,0]
	global_store_dwordx4 v[36:37], v[44:47], off nt
	v_exp_f32_e32 v37, v42
	v_pk_mul_f32 v[40:41], v[34:35], v[38:39] op_sel_hi:[1,0]
	v_mul_f32_e32 v36, v149, v149
	v_exp_f32_e32 v32, v40
	v_add_f32_e32 v37, 1.0, v37
	v_rcp_f32_e32 v42, v37
	v_exp_f32_e32 v37, v43
	v_exp_f32_e32 v33, v41
	v_add_f32_e32 v32, 1.0, v32
	v_rcp_f32_e32 v32, v32
	v_add_f32_e32 v37, 1.0, v37
	v_add_f32_e32 v33, 1.0, v33
	v_rcp_f32_e32 v43, v37
	v_rcp_f32_e32 v33, v33
	v_pk_mul_f32 v[28:29], v[28:29], v[36:37] op_sel_hi:[1,0]
	v_pk_mul_f32 v[30:31], v[30:31], v[36:37] op_sel_hi:[1,0]
	v_pk_mul_f32 v[28:29], v[28:29], v[42:43]
	v_pk_mul_f32 v[30:31], v[30:31], v[32:33]
	v_cvt_pk_bf16_f32 v28, v28, v29
	v_cvt_pk_bf16_f32 v29, v30, v31
	v_pk_mul_f32 v[30:31], v[26:27], v[38:39] op_sel_hi:[1,0]
	v_pk_mul_f32 v[32:33], v[24:25], v[38:39] op_sel_hi:[1,0]
	v_exp_f32_e32 v24, v30
	v_exp_f32_e32 v32, v32
	v_exp_f32_e32 v33, v33
	v_exp_f32_e32 v25, v31
	v_add_f32_e32 v24, 1.0, v24
	v_add_f32_e32 v32, 1.0, v32
	v_add_f32_e32 v33, 1.0, v33
	v_add_f32_e32 v25, 1.0, v25
	v_rcp_f32_e32 v32, v32
	v_rcp_f32_e32 v33, v33
	v_rcp_f32_e32 v24, v24
	v_rcp_f32_e32 v25, v25
	v_pk_mul_f32 v[20:21], v[20:21], v[36:37] op_sel_hi:[1,0]
	v_pk_mul_f32 v[22:23], v[22:23], v[36:37] op_sel_hi:[1,0]
	v_pk_mul_f32 v[20:21], v[20:21], v[32:33]
	v_pk_mul_f32 v[22:23], v[22:23], v[24:25]
	v_cvt_pk_bf16_f32 v30, v20, v21
	v_cvt_pk_bf16_f32 v31, v22, v23
	v_mad_i64_i32 v[20:21], s[2:3], v148, s33, v[116:117]
	v_mul_f32_e32 v22, 0xbfb8aa3b, v132
	v_lshl_add_u64 v[20:21], v[20:21], 0, v[118:119]
	v_pk_mul_f32 v[26:27], v[16:17], v[22:23] op_sel_hi:[1,0]
	global_store_dwordx4 v[20:21], v[28:31], off nt
	v_exp_f32_e32 v21, v26
	v_pk_mul_f32 v[24:25], v[18:19], v[22:23] op_sel_hi:[1,0]
	v_mul_f32_e32 v20, v132, v132
	v_exp_f32_e32 v16, v24
	v_add_f32_e32 v21, 1.0, v21
	v_rcp_f32_e32 v26, v21
	v_exp_f32_e32 v21, v27
	v_exp_f32_e32 v17, v25
	v_add_f32_e32 v16, 1.0, v16
	v_rcp_f32_e32 v16, v16
	v_add_f32_e32 v21, 1.0, v21
	v_add_f32_e32 v17, 1.0, v17
	v_rcp_f32_e32 v27, v21
	v_rcp_f32_e32 v17, v17
	v_pk_mul_f32 v[12:13], v[12:13], v[20:21] op_sel_hi:[1,0]
	v_pk_mul_f32 v[14:15], v[14:15], v[20:21] op_sel_hi:[1,0]
	v_pk_mul_f32 v[12:13], v[12:13], v[26:27]
	v_pk_mul_f32 v[14:15], v[14:15], v[16:17]
	v_pk_mul_f32 v[16:17], v[8:9], v[22:23] op_sel_hi:[1,0]
	v_cvt_pk_bf16_f32 v12, v12, v13
	v_cvt_pk_bf16_f32 v13, v14, v15
	v_pk_mul_f32 v[14:15], v[10:11], v[22:23] op_sel_hi:[1,0]
	v_exp_f32_e32 v16, v16
	v_exp_f32_e32 v17, v17
	v_exp_f32_e32 v8, v14
	v_exp_f32_e32 v9, v15
	v_add_f32_e32 v16, 1.0, v16
	v_add_f32_e32 v17, 1.0, v17
	v_rcp_f32_e32 v16, v16
	v_rcp_f32_e32 v17, v17
	v_add_f32_e32 v8, 1.0, v8
	v_add_f32_e32 v9, 1.0, v9
	v_rcp_f32_e32 v8, v8
	v_rcp_f32_e32 v9, v9
	v_pk_mul_f32 v[4:5], v[4:5], v[20:21] op_sel_hi:[1,0]
	v_pk_mul_f32 v[6:7], v[6:7], v[20:21] op_sel_hi:[1,0]
	v_pk_mul_f32 v[4:5], v[4:5], v[16:17]
	v_pk_mul_f32 v[6:7], v[6:7], v[8:9]
	v_cvt_pk_bf16_f32 v14, v4, v5
	v_mad_i64_i32 v[4:5], s[2:3], v146, s33, v[116:117]
	v_cvt_pk_bf16_f32 v15, v6, v7
	v_lshl_add_u64 v[4:5], v[4:5], 0, v[118:119]
	s_mov_b64 s[2:3], -1
	global_store_dwordx4 v[4:5], v[12:15], off nt
	s_cbranch_vccnz .LBB0_20
	s_andn2_b64 vcc, exec, s[10:11]
	s_cbranch_vccnz .LBB0_19
	s_barrier
	s_branch .LBB0_19
